# v093 + the one-time grid-barrier census issues its 16 counter loads back to back instead of one round trip at a time
# baseline (speedup 1.0000x reference)
; __device__ __forceinline__ unsigned xb_ld(unsigned* p)              { return __hip_atomic_load(p, __ATOMIC_RELAXED, __HIP_MEMORY_SCOPE_AGENT); }
; __device__ __forceinline__ void xcd_barrier_complete(unsigned* bar, unsigned x, unsigned& nloc, unsigned& nx) {
;     const unsigned G = gridDim.x * gridDim.y * gridDim.z;
;     unsigned sum, cnt, mine, sp = 0u;
;     for (;;) {
;         sum = 0u; cnt = 0u; mine = 0u;
; #pragma unroll
;         for (unsigned j = 0; j < 16; ++j) { const unsigned c = xb_ld(&bar[XB_XCNT(j)]); sum += c; cnt += (c > 0u) ? 1u : 0u; mine = (j == x) ? c : mine; }
;         if (sum == G) break;
;         __builtin_amdgcn_s_sleep(1);
;         if ((++sp & 255u) == 0u) { if (xb_ld(&bar[XB_TMO])) break; if (sp > XB_SPIN_CAP) { atomicAdd(&bar[XB_TMO], 1u); break; } }
;     }
;     nloc = mine > 0u ? mine : 1u; nx = cnt > 0u ? cnt : 1u;
; }
.LBB0_123:
	s_waitcnt lgkmcnt(0)
	s_mov_b64 s[18:19], -1
	s_mov_b64 s[20:21], -1
	global_load_dword v0, v16, s[48:49] sc1
	global_load_dword v1, v16, s[48:49] offset:256 sc1
	global_load_dword v2, v16, s[48:49] offset:512 sc1
	global_load_dword v3, v16, s[48:49] offset:768 sc1
	global_load_dword v4, v16, s[48:49] offset:1024 sc1
	global_load_dword v5, v16, s[48:49] offset:1280 sc1
	global_load_dword v6, v16, s[48:49] offset:1536 sc1
	global_load_dword v7, v16, s[48:49] offset:1792 sc1
	global_load_dword v8, v16, s[48:49] offset:2048 sc1
	global_load_dword v9, v16, s[48:49] offset:2304 sc1
	global_load_dword v10, v16, s[48:49] offset:2560 sc1
	global_load_dword v11, v16, s[48:49] offset:2816 sc1
	global_load_dword v12, v16, s[48:49] offset:3072 sc1
	global_load_dword v13, v16, s[48:49] offset:3328 sc1
	global_load_dword v14, v16, s[12:13] sc1
	global_load_dword v15, v16, s[14:15] sc1
	v_readlane_b32 s4, v253, 29
	v_readlane_b32 s5, v253, 30
	s_waitcnt vmcnt(0)
	v_add_u32_e32 v17, v1, v0
	v_add_u32_e32 v17, v17, v2
	v_add_u32_e32 v17, v17, v3
	v_add_u32_e32 v17, v17, v4
	v_add_u32_e32 v17, v17, v5
	v_add_u32_e32 v17, v17, v6
	v_add_u32_e32 v17, v17, v7
	v_add_u32_e32 v17, v17, v8
	v_add_u32_e32 v17, v17, v9
	v_add_u32_e32 v17, v17, v10
	v_add_u32_e32 v17, v17, v11
	v_add_u32_e32 v17, v17, v12
	v_add_u32_e32 v17, v17, v13
	v_add_u32_e32 v17, v17, v14
	v_add_u32_e32 v17, v17, v15
	v_cmp_eq_u32_e32 vcc, s94, v17
	s_cbranch_vccnz .LBB0_122
	s_and_b32 s3, s2, 0xff
	s_cmp_eq_u32 s3, 0
	s_mov_b64 s[22:23], -1
	s_sleep 1
	s_cbranch_scc0 .LBB0_127
	v_readlane_b32 s4, v253, 3
	v_readlane_b32 s5, v253, 4
	s_nop 4
	global_load_dword v17, v16, s[4:5] sc1
	s_waitcnt vmcnt(0)
	v_cmp_eq_u32_e32 vcc, 0, v17
	s_cbranch_vccnz .LBB0_129
	s_mov_b64 s[22:23], 0
